# retention state scan: fragments of the next MFMA step read before the current MFMA (two register sets)
# speedup vs baseline: 1.0148x; 1.0056x over previous
.Lrs_skipld:
	ds_read_b64_tr_b16 v[146:147], v75
	ds_read_b64_tr_b16 v[148:149], v75 offset:1280
	ds_read_b64_tr_b16 v[150:151], v74 offset:40960
	ds_read_b64_tr_b16 v[152:153], v74 offset:41728
	ds_read_b64_tr_b16 v[154:155], v75 offset:5120
	ds_read_b64_tr_b16 v[156:157], v75 offset:6400
	ds_read_b64_tr_b16 v[158:159], v74 offset:44032
	ds_read_b64_tr_b16 v[160:161], v74 offset:44800
	v_mov_b32_e32 v51, v50
	v_pk_mul_f32 v[16:17], v[50:51], v[16:17]
	v_pk_mul_f32 v[14:15], v[50:51], v[14:15]
	v_pk_mul_f32 v[12:13], v[50:51], v[12:13]
	v_pk_mul_f32 v[10:11], v[50:51], v[10:11]
	v_pk_mul_f32 v[8:9], v[50:51], v[8:9]
	v_pk_mul_f32 v[6:7], v[50:51], v[6:7]
	v_pk_mul_f32 v[4:5], v[50:51], v[4:5]
	v_pk_mul_f32 v[2:3], v[52:53], v[2:3]
	s_nop 0
	s_nop 0
	s_cmp_lg_u32 s16, 0x7c0000
	s_waitcnt lgkmcnt(4)
	v_mfma_f32_32x32x16_bf16 v[2:17], v[146:149], v[150:153], v[2:17]
	ds_read_b64_tr_b16 v[146:147], v75 offset:10240
	ds_read_b64_tr_b16 v[148:149], v75 offset:11520
	ds_read_b64_tr_b16 v[150:151], v74 offset:47104
	ds_read_b64_tr_b16 v[152:153], v74 offset:47872
	s_waitcnt lgkmcnt(4)
	v_mfma_f32_32x32x16_bf16 v[2:17], v[154:157], v[158:161], v[2:17]
	ds_read_b64_tr_b16 v[154:155], v75 offset:15360
	ds_read_b64_tr_b16 v[156:157], v75 offset:16640
	ds_read_b64_tr_b16 v[158:159], v74 offset:50176
	ds_read_b64_tr_b16 v[160:161], v74 offset:50944
	s_waitcnt lgkmcnt(4)
	v_mfma_f32_32x32x16_bf16 v[2:17], v[146:149], v[150:153], v[2:17]
	ds_read_b64_tr_b16 v[146:147], v75 offset:20480
	ds_read_b64_tr_b16 v[148:149], v75 offset:21760
	ds_read_b64_tr_b16 v[150:151], v74 offset:53248
	ds_read_b64_tr_b16 v[152:153], v74 offset:54016
	s_waitcnt lgkmcnt(4)
	v_mfma_f32_32x32x16_bf16 v[2:17], v[154:157], v[158:161], v[2:17]
	ds_read_b64_tr_b16 v[154:155], v75 offset:25600
	ds_read_b64_tr_b16 v[156:157], v75 offset:26880
	ds_read_b64_tr_b16 v[158:159], v74 offset:56320
	ds_read_b64_tr_b16 v[160:161], v74 offset:57088
	s_waitcnt lgkmcnt(4)
	v_mfma_f32_32x32x16_bf16 v[2:17], v[146:149], v[150:153], v[2:17]
	ds_read_b64_tr_b16 v[146:147], v75 offset:30720
	ds_read_b64_tr_b16 v[148:149], v75 offset:32000
	ds_read_b64_tr_b16 v[150:151], v74 offset:59392
	ds_read_b64_tr_b16 v[152:153], v74 offset:60160
	s_waitcnt lgkmcnt(4)
	v_mfma_f32_32x32x16_bf16 v[2:17], v[154:157], v[158:161], v[2:17]
	ds_read_b64_tr_b16 v[154:155], v75 offset:35840
	ds_read_b64_tr_b16 v[156:157], v75 offset:37120
	ds_read_b64_tr_b16 v[158:159], v74 offset:62464
	ds_read_b64_tr_b16 v[160:161], v74 offset:63232
	s_waitcnt lgkmcnt(4)
	v_mfma_f32_32x32x16_bf16 v[2:17], v[146:149], v[150:153], v[2:17]
	s_waitcnt lgkmcnt(0)
	s_barrier
	v_mfma_f32_32x32x16_bf16 v[2:17], v[154:157], v[158:161], v[2:17]
	s_cbranch_scc1 .LBB0_570
	s_waitcnt vmcnt(21)
	ds_write_b128 v78, v[22:25]
	s_waitcnt vmcnt(20)
	ds_write_b128 v79, v[26:29]
	s_waitcnt vmcnt(19)
	ds_write_b128 v80, v[30:33]
	s_waitcnt vmcnt(18)
	ds_write_b128 v81, v[38:41]
	s_waitcnt vmcnt(17)
	v_lshlrev_b32_e32 v22, 16, v34
	v_and_b32_e32 v23, 0xffff0000, v34
	v_lshlrev_b32_e32 v24, 16, v35
	v_and_b32_e32 v25, 0xffff0000, v35
	v_pk_mul_f32 v[22:23], v[56:57], v[22:23]
	v_pk_mul_f32 v[24:25], v[56:57], v[24:25]
	v_cvt_pk_bf16_f32 v22, v22, v23
	v_cvt_pk_bf16_f32 v23, v24, v25
	v_lshlrev_b32_e32 v24, 16, v36
	v_and_b32_e32 v25, 0xffff0000, v36
	v_lshlrev_b32_e32 v26, 16, v37
	v_and_b32_e32 v27, 0xffff0000, v37
	s_add_u32 s16, s12, s8
	v_pk_mul_f32 v[24:25], v[56:57], v[24:25]
	v_pk_mul_f32 v[26:27], v[56:57], v[26:27]
	s_addc_u32 s17, s13, 0
	v_cvt_pk_bf16_f32 v24, v24, v25
	v_cvt_pk_bf16_f32 v25, v26, v27
	s_or_b32 s14, s14, 31
	ds_write_b128 v77, v[22:25] offset:40960
	s_waitcnt vmcnt(16)
	v_lshlrev_b32_e32 v22, 16, v18
	v_and_b32_e32 v23, 0xffff0000, v18
	s_ashr_i32 s15, s14, 31
	v_readlane_b32 s48, v251, 35
	s_lshl_b64 s[16:17], s[16:17], 10
	v_pk_mul_f32 v[22:23], v[54:55], v[22:23]
	s_lshl_b64 s[14:15], s[14:15], 18
	v_readlane_b32 s58, v251, 45
	v_cvt_pk_bf16_f32 v18, v22, v23
	v_lshlrev_b32_e32 v22, 16, v19
	v_and_b32_e32 v23, 0xffff0000, v19
	v_readlane_b32 s59, v251, 46
	s_add_u32 s11, s58, s14
	v_pk_mul_f32 v[22:23], v[54:55], v[22:23]
	s_addc_u32 s14, s59, s15
	v_cvt_pk_bf16_f32 v19, v22, v23
	v_lshlrev_b32_e32 v22, 16, v20
	v_and_b32_e32 v23, 0xffff0000, v20
	s_add_u32 s11, s11, s16
	v_pk_mul_f32 v[22:23], v[54:55], v[22:23]
	s_addc_u32 s14, s14, s17
	s_lshl_b32 s15, s37, 1
	v_cvt_pk_bf16_f32 v20, v22, v23
	v_lshlrev_b32_e32 v22, 16, v21
	v_and_b32_e32 v23, 0xffff0000, v21
	s_add_u32 s11, s11, s15
	v_pk_mul_f32 v[22:23], v[54:55], v[22:23]
	s_addc_u32 s15, s14, 0
	s_lshl_b32 s14, s36, 1
	v_cvt_pk_bf16_f32 v21, v22, v23
	s_add_u32 s14, s11, s14
	ds_write_b128 v76, v[18:21] offset:40960
	s_addc_u32 s15, s15, 0
	v_lshlrev_b32_e32 v18, 1, v48
	v_mov_b32_e32 v19, v47
	v_lshl_add_u64 v[76:77], s[14:15], 0, v[18:19]
	v_cvt_pk_bf16_f32 v20, v2, s0
	v_lshl_add_u64 v[18:19], v[76:77], 0, v[46:47]
	s_waitcnt lgkmcnt(0)
	s_barrier
	global_store_short v[18:19], v20, off
	v_cvt_pk_bf16_f32 v20, v3, s0
	global_store_short v[18:19], v20, off offset:1024
	v_cvt_pk_bf16_f32 v20, v4, s0
	v_or_b32_e32 v82, 0x2000, v46
	v_mov_b32_e32 v83, v47
	global_store_short v[18:19], v20, off offset:2048
	v_cvt_pk_bf16_f32 v20, v5, s0
	v_or_b32_e32 v84, 0x2400, v46
	v_mov_b32_e32 v85, v47
	global_store_short v[18:19], v20, off offset:3072
	v_cvt_pk_bf16_f32 v20, v6, s0
	v_lshl_add_u64 v[18:19], v[76:77], 0, v[82:83]
	v_or_b32_e32 v86, 0x2800, v46
	v_mov_b32_e32 v87, v47
	global_store_short v[18:19], v20, off
	v_cvt_pk_bf16_f32 v20, v7, s0
	v_lshl_add_u64 v[18:19], v[76:77], 0, v[84:85]
	global_store_short v[18:19], v20, off
	v_cvt_pk_bf16_f32 v20, v8, s0
	v_lshl_add_u64 v[18:19], v[76:77], 0, v[86:87]
	global_store_short v[18:19], v20, off
	v_pk_mul_f32 v[32:33], v[50:51], v[16:17]
	v_pk_mul_f32 v[30:31], v[50:51], v[14:15]
	v_pk_mul_f32 v[28:29], v[50:51], v[12:13]
	v_pk_mul_f32 v[26:27], v[50:51], v[10:11]
	v_pk_mul_f32 v[24:25], v[50:51], v[8:9]
	v_pk_mul_f32 v[22:23], v[50:51], v[6:7]
	v_pk_mul_f32 v[20:21], v[50:51], v[4:5]
	v_pk_mul_f32 v[18:19], v[52:53], v[2:3]
	ds_read_b64_tr_b16 v[2:3], v75
	ds_read_b64_tr_b16 v[4:5], v75 offset:1280
	ds_read_b64_tr_b16 v[34:35], v75 offset:5120
	ds_read_b64_tr_b16 v[36:37], v75 offset:6400
	ds_read_b64_tr_b16 v[38:39], v74 offset:40960
	ds_read_b64_tr_b16 v[40:41], v74 offset:41728
	ds_read_b64_tr_b16 v[50:51], v74 offset:44032
	ds_read_b64_tr_b16 v[52:53], v74 offset:44800
	ds_read_b64_tr_b16 v[54:55], v75 offset:35840
	ds_read_b64_tr_b16 v[56:57], v75 offset:37120
	s_waitcnt lgkmcnt(4)
	v_mfma_f32_32x32x16_bf16 v[18:33], v[2:5], v[38:41], v[18:33]
	v_or_b32_e32 v70, 0x2c00, v46
	v_mov_b32_e32 v71, v47
	v_cvt_pk_bf16_f32 v4, v9, s0
	v_lshl_add_u64 v[2:3], v[76:77], 0, v[70:71]
	global_store_short v[2:3], v4, off
	ds_read_b64_tr_b16 v[2:3], v75 offset:10240
	ds_read_b64_tr_b16 v[4:5], v75 offset:11520
	v_or_b32_e32 v68, 0x4000, v46
	s_waitcnt lgkmcnt(4)
	v_mfma_f32_32x32x16_bf16 v[18:33], v[34:37], v[50:53], v[18:33]
	v_mov_b32_e32 v69, v47
	v_cvt_pk_bf16_f32 v8, v10, s0
	v_lshl_add_u64 v[6:7], v[76:77], 0, v[68:69]
	global_store_short v[6:7], v8, off
	ds_read_b64_tr_b16 v[6:7], v74 offset:47104
	ds_read_b64_tr_b16 v[8:9], v74 offset:47872
	ds_read_b64_tr_b16 v[34:35], v75 offset:15360
	ds_read_b64_tr_b16 v[36:37], v75 offset:16640
	ds_read_b64_tr_b16 v[38:39], v74 offset:50176
	ds_read_b64_tr_b16 v[40:41], v74 offset:50944
	v_or_b32_e32 v66, 0x4400, v46
	v_mov_b32_e32 v67, v47
	s_waitcnt lgkmcnt(4)
	v_mfma_f32_32x32x16_bf16 v[18:33], v[2:5], v[6:9], v[18:33]
	v_cvt_pk_bf16_f32 v4, v11, s0
	v_lshl_add_u64 v[2:3], v[76:77], 0, v[66:67]
	global_store_short v[2:3], v4, off
	ds_read_b64_tr_b16 v[2:3], v75 offset:20480
	ds_read_b64_tr_b16 v[4:5], v75 offset:21760
	v_or_b32_e32 v64, 0x4800, v46
	v_mov_b32_e32 v65, v47
	v_cvt_pk_bf16_f32 v8, v12, s0
	s_waitcnt lgkmcnt(2)
	v_mfma_f32_32x32x16_bf16 v[18:33], v[34:37], v[38:41], v[18:33]
	v_lshl_add_u64 v[6:7], v[76:77], 0, v[64:65]
	global_store_short v[6:7], v8, off
	ds_read_b64_tr_b16 v[6:7], v74 offset:53248
	ds_read_b64_tr_b16 v[8:9], v74 offset:54016
	ds_read_b64_tr_b16 v[34:35], v75 offset:25600
	ds_read_b64_tr_b16 v[36:37], v75 offset:26880
	ds_read_b64_tr_b16 v[38:39], v74 offset:56320
	ds_read_b64_tr_b16 v[40:41], v74 offset:57088
	v_or_b32_e32 v62, 0x4c00, v46
	v_mov_b32_e32 v63, v47
	v_or_b32_e32 v60, 0x6000, v46
	v_mov_b32_e32 v61, v47
	s_waitcnt lgkmcnt(4)
	v_mfma_f32_32x32x16_bf16 v[18:33], v[2:5], v[6:9], v[18:33]
	v_cvt_pk_bf16_f32 v4, v13, s0
	v_lshl_add_u64 v[2:3], v[76:77], 0, v[62:63]
	global_store_short v[2:3], v4, off
	v_cvt_pk_bf16_f32 v8, v14, s0
	v_lshl_add_u64 v[6:7], v[76:77], 0, v[60:61]
	ds_read_b64_tr_b16 v[2:3], v75 offset:30720
	ds_read_b64_tr_b16 v[4:5], v75 offset:32000
	global_store_short v[6:7], v8, off
	s_waitcnt lgkmcnt(2)
	v_mfma_f32_32x32x16_bf16 v[18:33], v[34:37], v[38:41], v[18:33]
	ds_read_b64_tr_b16 v[6:7], v74 offset:59392
	ds_read_b64_tr_b16 v[8:9], v74 offset:60160
	s_ashr_i32 s11, s10, 31
	s_lshl_b64 s[10:11], s[10:11], 8
	s_or_b64 s[10:11], s[10:11], s[8:9]
	ds_read_b64_tr_b16 v[10:11], v74 offset:62464
	ds_read_b64_tr_b16 v[12:13], v74 offset:63232
	s_add_u32 s10, s10, s12
	v_readlane_b32 s49, v251, 36
	s_waitcnt lgkmcnt(2)
	v_mfma_f32_32x32x16_bf16 v[18:33], v[2:5], v[6:9], v[18:33]
	v_readlane_b32 s50, v251, 37
	v_readlane_b32 s51, v251, 38
	v_readlane_b32 s52, v251, 39
	v_readlane_b32 s53, v251, 40
	v_readlane_b32 s54, v251, 41
	v_readlane_b32 s55, v251, 42
	s_addc_u32 s11, s11, s13
	s_lshl_b64 s[10:11], s[10:11], 11
	v_readlane_b32 s40, v253, 0
	v_readlane_b32 s41, v253, 1
	s_add_u32 s8, s40, s10
	s_addc_u32 s10, s41, s11
	s_lshl_b32 s11, s37, 2
	s_waitcnt lgkmcnt(0)
	v_mfma_f32_32x32x16_bf16 v[18:33], v[54:57], v[10:13], v[18:33]
	s_add_u32 s8, s8, s11
	v_or_b32_e32 v44, 0x6800, v46
	v_mov_b32_e32 v45, v47
	s_addc_u32 s11, s10, 0
	s_lshl_b32 s10, s36, 2
	v_or_b32_e32 v42, 0x6c00, v46
	v_mov_b32_e32 v43, v47
	v_cvt_pk_bf16_f32 v4, v16, s0
	v_lshl_add_u64 v[2:3], v[76:77], 0, v[44:45]
	s_add_u32 s10, s8, s10
	v_or_b32_e32 v58, 0x6400, v46
	global_store_short v[2:3], v4, off
	v_cvt_pk_bf16_f32 v4, v17, s0
	v_lshl_add_u64 v[2:3], v[76:77], 0, v[42:43]
	s_addc_u32 s11, s11, 0
	v_lshlrev_b32_e32 v46, 2, v48
	global_store_short v[2:3], v4, off
	v_lshl_add_u64 v[2:3], s[10:11], 0, v[46:47]
	v_lshlrev_b32_e32 v46, 13, v73
	v_lshl_add_u64 v[2:3], v[2:3], 0, v[46:47]
	s_movk_i32 s8, 0x1000
	v_mov_b32_e32 v59, v47
	v_add_co_u32_e32 v4, vcc, s8, v2
	v_cvt_pk_bf16_f32 v34, v15, s0
	v_lshl_add_u64 v[14:15], v[76:77], 0, v[58:59]
	v_addc_co_u32_e32 v5, vcc, 0, v3, vcc
	global_store_short v[14:15], v34, off
	s_barrier
	global_store_dword v[2:3], v18, off
	global_store_dword v[2:3], v19, off offset:2048
	global_store_dword v[4:5], v20, off
	global_store_dword v[4:5], v21, off offset:2048
	v_add_co_u32_e32 v4, vcc, s34, v2
	s_movk_i32 s8, 0x5000
	s_nop 0
	v_addc_co_u32_e32 v5, vcc, 0, v3, vcc
	v_add_co_u32_e32 v6, vcc, s8, v2
	s_mov_b32 s8, 0x8000
	s_nop 0
	v_addc_co_u32_e32 v7, vcc, 0, v3, vcc
	global_store_dword v[6:7], v22, off offset:-4096
	global_store_dword v[4:5], v23, off offset:2048
	global_store_dword v[6:7], v24, off
	global_store_dword v[6:7], v25, off offset:2048
	v_add_co_u32_e32 v4, vcc, s8, v2
	s_mov_b32 s8, 0x9000
	s_nop 0
	v_addc_co_u32_e32 v5, vcc, 0, v3, vcc
	v_add_co_u32_e32 v6, vcc, s8, v2
	s_mov_b32 s8, 0xc000
	s_nop 0
	v_addc_co_u32_e32 v7, vcc, 0, v3, vcc
	global_store_dword v[6:7], v26, off offset:-4096
	global_store_dword v[4:5], v27, off offset:2048
	global_store_dword v[6:7], v28, off
	global_store_dword v[6:7], v29, off offset:2048
	v_add_co_u32_e32 v4, vcc, s8, v2
	s_add_i32 s35, s35, s88
	s_nop 0
	v_addc_co_u32_e32 v5, vcc, 0, v3, vcc
	v_add_co_u32_e32 v2, vcc, 0xd000, v2
	s_add_i32 s24, s24, s25
	s_add_i32 s26, s26, s27
	v_addc_co_u32_e32 v3, vcc, 0, v3, vcc
	s_cmpk_gt_i32 s35, 0xff
	v_readlane_b32 s56, v251, 43
	v_readlane_b32 s57, v251, 44
	v_readlane_b32 s60, v251, 47
	v_readlane_b32 s61, v251, 48
	v_readlane_b32 s62, v251, 49
	v_readlane_b32 s63, v251, 50
	v_readlane_b32 s42, v253, 2
	v_readlane_b32 s43, v253, 3
	v_readlane_b32 s44, v253, 4
	v_readlane_b32 s45, v253, 5
	v_readlane_b32 s46, v253, 6
	v_readlane_b32 s47, v253, 7
	v_readlane_b32 s48, v253, 8
	v_readlane_b32 s49, v253, 9
	v_readlane_b32 s50, v253, 10
	v_readlane_b32 s51, v253, 11
	v_readlane_b32 s52, v253, 12
	v_readlane_b32 s53, v253, 13
	v_readlane_b32 s54, v253, 14
	v_readlane_b32 s55, v253, 15
	global_store_dword v[4:5], v30, off
	global_store_dword v[4:5], v31, off offset:2048
	global_store_dword v[2:3], v32, off
	global_store_dword v[2:3], v33, off offset:2048
	s_cbranch_scc0 .LBB0_569
